# v47: v44 + accumulator zeroing moved ahead of the prologue waits in all five restructured GEMM loops
# speedup vs baseline: 1.0646x; 1.0039x over previous
; #define STAGE(P, BASE, br, kt) do { const long _g = (long)(br) * K + (long)(kt) * 64; \
;     _Pragma("unroll") for (int _i = 0; _i < 2; ++_i) { const int _b = tidx * 16 + _i * 8192; int _r, _c; stage_rc8(_b, _r, _c); \
;       __builtin_amdgcn_global_load_lds((const unsigned*)(BASE + _g + (long)_r * K + _c), (LAS unsigned*)((LAS char*)(P) + _b), 16, 0, 0); } } while (0)
; #define BAR __builtin_amdgcn_s_barrier()
; template <class FL, class FS>
; DI void gemm8_tile(char* shmc, const bf16_t* __restrict__ A, const bf16_t* __restrict__ Bt, const int K, const int brow, const int bcol, FL fl, FS fs) {
;     ...
; #pragma unroll
;   for (int a = 0; a < 2; ++a)
; #pragma unroll
;     for (int b = 0; b < 2; ++b)
; #pragma unroll
;       for (int m = 0; m < 4; ++m)
; #pragma unroll
;         for (int n = 0; n < 2; ++n) acc[a][b][m][n] = (f32x4){0.f, 0.f, 0.f, 0.f};
;   bf16x8 At[4][2], B0[2][2], B1[2][2];
;   const int nt = K / 64;
;   STAGE(SB(0, 0), Bt, bcol, 0); STAGE(SA(0, 0), A, brow, 0);
;   STAGE(SB(0, 1), Bt, bcol + HALF, 0); STAGE(SA(0, 1), A, brow + HALF, 0);
;   if (wr == 1) BAR;
.Lg1_epi_ret0:
	v_mov_b32_e32 v0, 0
	v_mov_b32_e32 v1, v0
	v_mov_b32_e32 v2, v0
	v_mov_b32_e32 v3, v0
	v_mov_b32_e32 v4, v0
	v_mov_b32_e32 v5, v0
	v_mov_b32_e32 v6, v0
	v_mov_b32_e32 v7, v0
	v_mov_b32_e32 v8, v0
	v_mov_b32_e32 v9, v0
	v_mov_b32_e32 v10, v0
	v_mov_b32_e32 v11, v0
	v_mov_b32_e32 v12, v0
	v_mov_b32_e32 v13, v0
	v_mov_b32_e32 v14, v0
	v_mov_b32_e32 v15, v0
	v_mov_b32_e32 v16, v0
	v_mov_b32_e32 v17, v0
	v_mov_b32_e32 v18, v0
	v_mov_b32_e32 v19, v0
	v_mov_b32_e32 v20, v0
	v_mov_b32_e32 v21, v0
	v_mov_b32_e32 v22, v0
	v_mov_b32_e32 v23, v0
	v_mov_b32_e32 v24, v0
	v_mov_b32_e32 v25, v0
	v_mov_b32_e32 v26, v0
	v_mov_b32_e32 v27, v0
	v_mov_b32_e32 v28, v0
	v_mov_b32_e32 v29, v0
	v_mov_b32_e32 v30, v0
	v_mov_b32_e32 v31, v0
	v_mov_b32_e32 v32, v0
	v_mov_b32_e32 v33, v0
	v_mov_b32_e32 v34, v0
	v_mov_b32_e32 v35, v0
	v_mov_b32_e32 v36, v0
	v_mov_b32_e32 v37, v0
	v_mov_b32_e32 v38, v0
	v_mov_b32_e32 v39, v0
	v_mov_b32_e32 v40, v0
	v_mov_b32_e32 v41, v0
	v_mov_b32_e32 v42, v0
	v_mov_b32_e32 v43, v0
	v_mov_b32_e32 v44, v0
	v_mov_b32_e32 v45, v0
	v_mov_b32_e32 v46, v0
	v_mov_b32_e32 v47, v0
	v_mov_b32_e32 v48, v0
	v_mov_b32_e32 v49, v0
	v_mov_b32_e32 v50, v0
	v_mov_b32_e32 v51, v0
	v_mov_b32_e32 v52, v0
	v_mov_b32_e32 v53, v0
	v_mov_b32_e32 v54, v0
	v_mov_b32_e32 v55, v0
	v_mov_b32_e32 v56, v0
	v_mov_b32_e32 v57, v0
	v_mov_b32_e32 v58, v0
	v_mov_b32_e32 v59, v0
	v_mov_b32_e32 v60, v0
	v_mov_b32_e32 v61, v0
	v_mov_b32_e32 v62, v0
	v_mov_b32_e32 v63, v0
	v_mov_b32_e32 v64, v0
	v_mov_b32_e32 v65, v0
	v_mov_b32_e32 v66, v0
	v_mov_b32_e32 v67, v0
	v_mov_b32_e32 v68, v0
	v_mov_b32_e32 v69, v0
	v_mov_b32_e32 v70, v0
	v_mov_b32_e32 v71, v0
	v_mov_b32_e32 v72, v0
	v_mov_b32_e32 v73, v0
	v_mov_b32_e32 v74, v0
	v_mov_b32_e32 v75, v0
	v_mov_b32_e32 v76, v0
	v_mov_b32_e32 v77, v0
	v_mov_b32_e32 v78, v0
	v_mov_b32_e32 v79, v0
	v_mov_b32_e32 v80, v0
	v_mov_b32_e32 v81, v0
	v_mov_b32_e32 v82, v0
	v_mov_b32_e32 v83, v0
	v_mov_b32_e32 v84, v0
	v_mov_b32_e32 v85, v0
	v_mov_b32_e32 v86, v0
	v_mov_b32_e32 v87, v0
	v_mov_b32_e32 v88, v0
	v_mov_b32_e32 v89, v0
	v_mov_b32_e32 v90, v0
	v_mov_b32_e32 v91, v0
	v_mov_b32_e32 v92, v0
	v_mov_b32_e32 v93, v0
	v_mov_b32_e32 v94, v0
	v_mov_b32_e32 v95, v0
	v_mov_b32_e32 v96, v0
	v_mov_b32_e32 v97, v0
	v_mov_b32_e32 v98, v0
	v_mov_b32_e32 v99, v0
	v_mov_b32_e32 v100, v0
	v_mov_b32_e32 v101, v0
	v_mov_b32_e32 v102, v0
	v_mov_b32_e32 v103, v0
	v_mov_b32_e32 v104, v0
	v_mov_b32_e32 v105, v0
	v_mov_b32_e32 v106, v0
	v_mov_b32_e32 v107, v0
	v_mov_b32_e32 v108, v0
	v_mov_b32_e32 v109, v0
	v_mov_b32_e32 v110, v0
	v_mov_b32_e32 v111, v0
	v_mov_b32_e32 v112, v0
	v_mov_b32_e32 v113, v0
	v_mov_b32_e32 v114, v0
	v_mov_b32_e32 v115, v0
	v_mov_b32_e32 v116, v0
	v_mov_b32_e32 v117, v0
	v_mov_b32_e32 v118, v0
	v_mov_b32_e32 v119, v0
	v_mov_b32_e32 v120, v0
	v_mov_b32_e32 v121, v0
	v_mov_b32_e32 v122, v0
	v_mov_b32_e32 v123, v0
	v_mov_b32_e32 v124, v0
	v_mov_b32_e32 v125, v0
	v_mov_b32_e32 v126, v0
	v_mov_b32_e32 v127, v0
	v_lshrrev_b32_e32 v222, 8, v182
	v_cmp_eq_u32_e32 vcc, 1, v222
	s_and_saveexec_b64 s[8:9], vcc
	s_cbranch_execz .Lg1_nba
	s_barrier

; #define STAGE(P, BASE, br, kt) do { const long _g = (long)(br) * K + (long)(kt) * 64; \
;     _Pragma("unroll") for (int _i = 0; _i < 2; ++_i) { const int _b = tidx * 16 + _i * 8192; int _r, _c; stage_rc8(_b, _r, _c); \
;       __builtin_amdgcn_global_load_lds((const unsigned*)(BASE + _g + (long)_r * K + _c), (LAS unsigned*)((LAS char*)(P) + _b), 16, 0, 0); } } while (0)
; #define WAIT_V(n) asm volatile("s_waitcnt vmcnt(" #n ")" ::: "memory")
; #define BAR __builtin_amdgcn_s_barrier()
; template <class FL, class FS>
; DI void gemm8_tile(char* shmc, const bf16_t* __restrict__ A, const bf16_t* __restrict__ Bt, const int K, const int brow, const int bcol, FL fl, FS fs) {
;     ...
;   if (wr == 1) BAR;
;   WAIT_V(4); BAR;
;   STAGE(SB(1, 0), Bt, bcol, 1); STAGE(SA(1, 0), A, brow, 1); STAGE(SB(1, 1), Bt, bcol + HALF, 1);
;   WAIT_V(6); BAR;
;   for (int t = 0; t < nt - 2; t += 2) {
.Lg1_zero:
	s_mov_b32 s0, -2
	s_barrier

; #define STAGE(P, BASE, br, kt) do { const long _g = (long)(br) * K + (long)(kt) * 64; \
;     _Pragma("unroll") for (int _i = 0; _i < 2; ++_i) { const int _b = tidx * 16 + _i * 8192; int _r, _c; stage_rc8(_b, _r, _c); \
;       __builtin_amdgcn_global_load_lds((const unsigned*)(BASE + _g + (long)_r * K + _c), (LAS unsigned*)((LAS char*)(P) + _b), 16, 0, 0); } } while (0)
; #define BAR __builtin_amdgcn_s_barrier()
; template <class FL, class FS>
; DI void gemm8_tile(char* shmc, const bf16_t* __restrict__ A, const bf16_t* __restrict__ Bt, const int K, const int brow, const int bcol, FL fl, FS fs) {
;     ...
; #pragma unroll
;   for (int a = 0; a < 2; ++a)
; #pragma unroll
;     for (int b = 0; b < 2; ++b)
; #pragma unroll
;       for (int m = 0; m < 4; ++m)
; #pragma unroll
;         for (int n = 0; n < 2; ++n) acc[a][b][m][n] = (f32x4){0.f, 0.f, 0.f, 0.f};
;   bf16x8 At[4][2], B0[2][2], B1[2][2];
;   const int nt = K / 64;
;   STAGE(SB(0, 0), Bt, bcol, 0); STAGE(SA(0, 0), A, brow, 0);
;   STAGE(SB(0, 1), Bt, bcol + HALF, 0); STAGE(SA(0, 1), A, brow + HALF, 0);
;   if (wr == 1) BAR;
.Lg2_epi_ret0:
	v_mov_b32_e32 v0, 0
	v_mov_b32_e32 v1, v0
	v_mov_b32_e32 v2, v0
	v_mov_b32_e32 v3, v0
	v_mov_b32_e32 v4, v0
	v_mov_b32_e32 v5, v0
	v_mov_b32_e32 v6, v0
	v_mov_b32_e32 v7, v0
	v_mov_b32_e32 v8, v0
	v_mov_b32_e32 v9, v0
	v_mov_b32_e32 v10, v0
	v_mov_b32_e32 v11, v0
	v_mov_b32_e32 v12, v0
	v_mov_b32_e32 v13, v0
	v_mov_b32_e32 v14, v0
	v_mov_b32_e32 v15, v0
	v_mov_b32_e32 v16, v0
	v_mov_b32_e32 v17, v0
	v_mov_b32_e32 v18, v0
	v_mov_b32_e32 v19, v0
	v_mov_b32_e32 v20, v0
	v_mov_b32_e32 v21, v0
	v_mov_b32_e32 v22, v0
	v_mov_b32_e32 v23, v0
	v_mov_b32_e32 v24, v0
	v_mov_b32_e32 v25, v0
	v_mov_b32_e32 v26, v0
	v_mov_b32_e32 v27, v0
	v_mov_b32_e32 v28, v0
	v_mov_b32_e32 v29, v0
	v_mov_b32_e32 v30, v0
	v_mov_b32_e32 v31, v0
	v_mov_b32_e32 v32, v0
	v_mov_b32_e32 v33, v0
	v_mov_b32_e32 v34, v0
	v_mov_b32_e32 v35, v0
	v_mov_b32_e32 v36, v0
	v_mov_b32_e32 v37, v0
	v_mov_b32_e32 v38, v0
	v_mov_b32_e32 v39, v0
	v_mov_b32_e32 v40, v0
	v_mov_b32_e32 v41, v0
	v_mov_b32_e32 v42, v0
	v_mov_b32_e32 v43, v0
	v_mov_b32_e32 v44, v0
	v_mov_b32_e32 v45, v0
	v_mov_b32_e32 v46, v0
	v_mov_b32_e32 v47, v0
	v_mov_b32_e32 v48, v0
	v_mov_b32_e32 v49, v0
	v_mov_b32_e32 v50, v0
	v_mov_b32_e32 v51, v0
	v_mov_b32_e32 v52, v0
	v_mov_b32_e32 v53, v0
	v_mov_b32_e32 v54, v0
	v_mov_b32_e32 v55, v0
	v_mov_b32_e32 v56, v0
	v_mov_b32_e32 v57, v0
	v_mov_b32_e32 v58, v0
	v_mov_b32_e32 v59, v0
	v_mov_b32_e32 v60, v0
	v_mov_b32_e32 v61, v0
	v_mov_b32_e32 v62, v0
	v_mov_b32_e32 v63, v0
	v_mov_b32_e32 v64, v0
	v_mov_b32_e32 v65, v0
	v_mov_b32_e32 v66, v0
	v_mov_b32_e32 v67, v0
	v_mov_b32_e32 v68, v0
	v_mov_b32_e32 v69, v0
	v_mov_b32_e32 v70, v0
	v_mov_b32_e32 v71, v0
	v_mov_b32_e32 v72, v0
	v_mov_b32_e32 v73, v0
	v_mov_b32_e32 v74, v0
	v_mov_b32_e32 v75, v0
	v_mov_b32_e32 v76, v0
	v_mov_b32_e32 v77, v0
	v_mov_b32_e32 v78, v0
	v_mov_b32_e32 v79, v0
	v_mov_b32_e32 v80, v0
	v_mov_b32_e32 v81, v0
	v_mov_b32_e32 v82, v0
	v_mov_b32_e32 v83, v0
	v_mov_b32_e32 v84, v0
	v_mov_b32_e32 v85, v0
	v_mov_b32_e32 v86, v0
	v_mov_b32_e32 v87, v0
	v_mov_b32_e32 v88, v0
	v_mov_b32_e32 v89, v0
	v_mov_b32_e32 v90, v0
	v_mov_b32_e32 v91, v0
	v_mov_b32_e32 v92, v0
	v_mov_b32_e32 v93, v0
	v_mov_b32_e32 v94, v0
	v_mov_b32_e32 v95, v0
	v_mov_b32_e32 v96, v0
	v_mov_b32_e32 v97, v0
	v_mov_b32_e32 v98, v0
	v_mov_b32_e32 v99, v0
	v_mov_b32_e32 v100, v0
	v_mov_b32_e32 v101, v0
	v_mov_b32_e32 v102, v0
	v_mov_b32_e32 v103, v0
	v_mov_b32_e32 v104, v0
	v_mov_b32_e32 v105, v0
	v_mov_b32_e32 v106, v0
	v_mov_b32_e32 v107, v0
	v_mov_b32_e32 v108, v0
	v_mov_b32_e32 v109, v0
	v_mov_b32_e32 v110, v0
	v_mov_b32_e32 v111, v0
	v_mov_b32_e32 v112, v0
	v_mov_b32_e32 v113, v0
	v_mov_b32_e32 v114, v0
	v_mov_b32_e32 v115, v0
	v_mov_b32_e32 v116, v0
	v_mov_b32_e32 v117, v0
	v_mov_b32_e32 v118, v0
	v_mov_b32_e32 v119, v0
	v_mov_b32_e32 v120, v0
	v_mov_b32_e32 v121, v0
	v_mov_b32_e32 v122, v0
	v_mov_b32_e32 v123, v0
	v_mov_b32_e32 v124, v0
	v_mov_b32_e32 v125, v0
	v_mov_b32_e32 v126, v0
	v_mov_b32_e32 v127, v0
	v_lshrrev_b32_e32 v222, 8, v182
	v_cmp_eq_u32_e32 vcc, 1, v222
	s_and_saveexec_b64 s[44:45], vcc
	s_cbranch_execz .Lg2_nba
	s_barrier

; #define STAGE(P, BASE, br, kt) do { const long _g = (long)(br) * K + (long)(kt) * 64; \
;     _Pragma("unroll") for (int _i = 0; _i < 2; ++_i) { const int _b = tidx * 16 + _i * 8192; int _r, _c; stage_rc8(_b, _r, _c); \
;       __builtin_amdgcn_global_load_lds((const unsigned*)(BASE + _g + (long)_r * K + _c), (LAS unsigned*)((LAS char*)(P) + _b), 16, 0, 0); } } while (0)
; #define BAR __builtin_amdgcn_s_barrier()
; template <class FL, class FS>
; DI void gemm8_tile(char* shmc, const bf16_t* __restrict__ A, const bf16_t* __restrict__ Bt, const int K, const int brow, const int bcol, FL fl, FS fs) {
;     ...
; #pragma unroll
;   for (int a = 0; a < 2; ++a)
; #pragma unroll
;     for (int b = 0; b < 2; ++b)
; #pragma unroll
;       for (int m = 0; m < 4; ++m)
; #pragma unroll
;         for (int n = 0; n < 2; ++n) acc[a][b][m][n] = (f32x4){0.f, 0.f, 0.f, 0.f};
;   bf16x8 At[4][2], B0[2][2], B1[2][2];
;   const int nt = K / 64;
;   STAGE(SB(0, 0), Bt, bcol, 0); STAGE(SA(0, 0), A, brow, 0);
;   STAGE(SB(0, 1), Bt, bcol + HALF, 0); STAGE(SA(0, 1), A, brow + HALF, 0);
;   if (wr == 1) BAR;
.Lg3_epi_ret0:
	v_mov_b32_e32 v0, 0
	v_mov_b32_e32 v1, v0
	v_mov_b32_e32 v2, v0
	v_mov_b32_e32 v3, v0
	v_mov_b32_e32 v4, v0
	v_mov_b32_e32 v5, v0
	v_mov_b32_e32 v6, v0
	v_mov_b32_e32 v7, v0
	v_mov_b32_e32 v8, v0
	v_mov_b32_e32 v9, v0
	v_mov_b32_e32 v10, v0
	v_mov_b32_e32 v11, v0
	v_mov_b32_e32 v12, v0
	v_mov_b32_e32 v13, v0
	v_mov_b32_e32 v14, v0
	v_mov_b32_e32 v15, v0
	v_mov_b32_e32 v16, v0
	v_mov_b32_e32 v17, v0
	v_mov_b32_e32 v18, v0
	v_mov_b32_e32 v19, v0
	v_mov_b32_e32 v20, v0
	v_mov_b32_e32 v21, v0
	v_mov_b32_e32 v22, v0
	v_mov_b32_e32 v23, v0
	v_mov_b32_e32 v24, v0
	v_mov_b32_e32 v25, v0
	v_mov_b32_e32 v26, v0
	v_mov_b32_e32 v27, v0
	v_mov_b32_e32 v28, v0
	v_mov_b32_e32 v29, v0
	v_mov_b32_e32 v30, v0
	v_mov_b32_e32 v31, v0
	v_mov_b32_e32 v32, v0
	v_mov_b32_e32 v33, v0
	v_mov_b32_e32 v34, v0
	v_mov_b32_e32 v35, v0
	v_mov_b32_e32 v36, v0
	v_mov_b32_e32 v37, v0
	v_mov_b32_e32 v38, v0
	v_mov_b32_e32 v39, v0
	v_mov_b32_e32 v40, v0
	v_mov_b32_e32 v41, v0
	v_mov_b32_e32 v42, v0
	v_mov_b32_e32 v43, v0
	v_mov_b32_e32 v44, v0
	v_mov_b32_e32 v45, v0
	v_mov_b32_e32 v46, v0
	v_mov_b32_e32 v47, v0
	v_mov_b32_e32 v48, v0
	v_mov_b32_e32 v49, v0
	v_mov_b32_e32 v50, v0
	v_mov_b32_e32 v51, v0
	v_mov_b32_e32 v52, v0
	v_mov_b32_e32 v53, v0
	v_mov_b32_e32 v54, v0
	v_mov_b32_e32 v55, v0
	v_mov_b32_e32 v56, v0
	v_mov_b32_e32 v57, v0
	v_mov_b32_e32 v58, v0
	v_mov_b32_e32 v59, v0
	v_mov_b32_e32 v60, v0
	v_mov_b32_e32 v61, v0
	v_mov_b32_e32 v62, v0
	v_mov_b32_e32 v63, v0
	v_mov_b32_e32 v64, v0
	v_mov_b32_e32 v65, v0
	v_mov_b32_e32 v66, v0
	v_mov_b32_e32 v67, v0
	v_mov_b32_e32 v68, v0
	v_mov_b32_e32 v69, v0
	v_mov_b32_e32 v70, v0
	v_mov_b32_e32 v71, v0
	v_mov_b32_e32 v72, v0
	v_mov_b32_e32 v73, v0
	v_mov_b32_e32 v74, v0
	v_mov_b32_e32 v75, v0
	v_mov_b32_e32 v76, v0
	v_mov_b32_e32 v77, v0
	v_mov_b32_e32 v78, v0
	v_mov_b32_e32 v79, v0
	v_mov_b32_e32 v80, v0
	v_mov_b32_e32 v81, v0
	v_mov_b32_e32 v82, v0
	v_mov_b32_e32 v83, v0
	v_mov_b32_e32 v84, v0
	v_mov_b32_e32 v85, v0
	v_mov_b32_e32 v86, v0
	v_mov_b32_e32 v87, v0
	v_mov_b32_e32 v88, v0
	v_mov_b32_e32 v89, v0
	v_mov_b32_e32 v90, v0
	v_mov_b32_e32 v91, v0
	v_mov_b32_e32 v92, v0
	v_mov_b32_e32 v93, v0
	v_mov_b32_e32 v94, v0
	v_mov_b32_e32 v95, v0
	v_mov_b32_e32 v96, v0
	v_mov_b32_e32 v97, v0
	v_mov_b32_e32 v98, v0
	v_mov_b32_e32 v99, v0
	v_mov_b32_e32 v100, v0
	v_mov_b32_e32 v101, v0
	v_mov_b32_e32 v102, v0
	v_mov_b32_e32 v103, v0
	v_mov_b32_e32 v104, v0
	v_mov_b32_e32 v105, v0
	v_mov_b32_e32 v106, v0
	v_mov_b32_e32 v107, v0
	v_mov_b32_e32 v108, v0
	v_mov_b32_e32 v109, v0
	v_mov_b32_e32 v110, v0
	v_mov_b32_e32 v111, v0
	v_mov_b32_e32 v112, v0
	v_mov_b32_e32 v113, v0
	v_mov_b32_e32 v114, v0
	v_mov_b32_e32 v115, v0
	v_mov_b32_e32 v116, v0
	v_mov_b32_e32 v117, v0
	v_mov_b32_e32 v118, v0
	v_mov_b32_e32 v119, v0
	v_mov_b32_e32 v120, v0
	v_mov_b32_e32 v121, v0
	v_mov_b32_e32 v122, v0
	v_mov_b32_e32 v123, v0
	v_mov_b32_e32 v124, v0
	v_mov_b32_e32 v125, v0
	v_mov_b32_e32 v126, v0
	v_mov_b32_e32 v127, v0
	v_lshrrev_b32_e32 v222, 8, v182
	v_cmp_eq_u32_e32 vcc, 1, v222
	s_and_saveexec_b64 s[4:5], vcc
	s_cbranch_execz .Lg3_nba
	s_barrier

; #define STAGE(P, BASE, br, kt) do { const long _g = (long)(br) * K + (long)(kt) * 64; \
;     _Pragma("unroll") for (int _i = 0; _i < 2; ++_i) { const int _b = tidx * 16 + _i * 8192; int _r, _c; stage_rc8(_b, _r, _c); \
;       __builtin_amdgcn_global_load_lds((const unsigned*)(BASE + _g + (long)_r * K + _c), (LAS unsigned*)((LAS char*)(P) + _b), 16, 0, 0); } } while (0)
; #define BAR __builtin_amdgcn_s_barrier()
; template <class FL, class FS>
; DI void gemm8_tile(char* shmc, const bf16_t* __restrict__ A, const bf16_t* __restrict__ Bt, const int K, const int brow, const int bcol, FL fl, FS fs) {
;     ...
; #pragma unroll
;   for (int a = 0; a < 2; ++a)
; #pragma unroll
;     for (int b = 0; b < 2; ++b)
; #pragma unroll
;       for (int m = 0; m < 4; ++m)
; #pragma unroll
;         for (int n = 0; n < 2; ++n) acc[a][b][m][n] = (f32x4){0.f, 0.f, 0.f, 0.f};
;   bf16x8 At[4][2], B0[2][2], B1[2][2];
;   const int nt = K / 64;
;   STAGE(SB(0, 0), Bt, bcol, 0); STAGE(SA(0, 0), A, brow, 0);
;   STAGE(SB(0, 1), Bt, bcol + HALF, 0); STAGE(SA(0, 1), A, brow + HALF, 0);
;   if (wr == 1) BAR;
.Lg5_epi_ret0:
	v_mov_b32_e32 v0, 0
	v_mov_b32_e32 v1, v0
	v_mov_b32_e32 v2, v0
	v_mov_b32_e32 v3, v0
	v_mov_b32_e32 v4, v0
	v_mov_b32_e32 v5, v0
	v_mov_b32_e32 v6, v0
	v_mov_b32_e32 v7, v0
	v_mov_b32_e32 v8, v0
	v_mov_b32_e32 v9, v0
	v_mov_b32_e32 v10, v0
	v_mov_b32_e32 v11, v0
	v_mov_b32_e32 v12, v0
	v_mov_b32_e32 v13, v0
	v_mov_b32_e32 v14, v0
	v_mov_b32_e32 v15, v0
	v_mov_b32_e32 v16, v0
	v_mov_b32_e32 v17, v0
	v_mov_b32_e32 v18, v0
	v_mov_b32_e32 v19, v0
	v_mov_b32_e32 v20, v0
	v_mov_b32_e32 v21, v0
	v_mov_b32_e32 v22, v0
	v_mov_b32_e32 v23, v0
	v_mov_b32_e32 v24, v0
	v_mov_b32_e32 v25, v0
	v_mov_b32_e32 v26, v0
	v_mov_b32_e32 v27, v0
	v_mov_b32_e32 v28, v0
	v_mov_b32_e32 v29, v0
	v_mov_b32_e32 v30, v0
	v_mov_b32_e32 v31, v0
	v_mov_b32_e32 v32, v0
	v_mov_b32_e32 v33, v0
	v_mov_b32_e32 v34, v0
	v_mov_b32_e32 v35, v0
	v_mov_b32_e32 v36, v0
	v_mov_b32_e32 v37, v0
	v_mov_b32_e32 v38, v0
	v_mov_b32_e32 v39, v0
	v_mov_b32_e32 v40, v0
	v_mov_b32_e32 v41, v0
	v_mov_b32_e32 v42, v0
	v_mov_b32_e32 v43, v0
	v_mov_b32_e32 v44, v0
	v_mov_b32_e32 v45, v0
	v_mov_b32_e32 v46, v0
	v_mov_b32_e32 v47, v0
	v_mov_b32_e32 v48, v0
	v_mov_b32_e32 v49, v0
	v_mov_b32_e32 v50, v0
	v_mov_b32_e32 v51, v0
	v_mov_b32_e32 v52, v0
	v_mov_b32_e32 v53, v0
	v_mov_b32_e32 v54, v0
	v_mov_b32_e32 v55, v0
	v_mov_b32_e32 v56, v0
	v_mov_b32_e32 v57, v0
	v_mov_b32_e32 v58, v0
	v_mov_b32_e32 v59, v0
	v_mov_b32_e32 v60, v0
	v_mov_b32_e32 v61, v0
	v_mov_b32_e32 v62, v0
	v_mov_b32_e32 v63, v0
	v_mov_b32_e32 v64, v0
	v_mov_b32_e32 v65, v0
	v_mov_b32_e32 v66, v0
	v_mov_b32_e32 v67, v0
	v_mov_b32_e32 v68, v0
	v_mov_b32_e32 v69, v0
	v_mov_b32_e32 v70, v0
	v_mov_b32_e32 v71, v0
	v_mov_b32_e32 v72, v0
	v_mov_b32_e32 v73, v0
	v_mov_b32_e32 v74, v0
	v_mov_b32_e32 v75, v0
	v_mov_b32_e32 v76, v0
	v_mov_b32_e32 v77, v0
	v_mov_b32_e32 v78, v0
	v_mov_b32_e32 v79, v0
	v_mov_b32_e32 v80, v0
	v_mov_b32_e32 v81, v0
	v_mov_b32_e32 v82, v0
	v_mov_b32_e32 v83, v0
	v_mov_b32_e32 v84, v0
	v_mov_b32_e32 v85, v0
	v_mov_b32_e32 v86, v0
	v_mov_b32_e32 v87, v0
	v_mov_b32_e32 v88, v0
	v_mov_b32_e32 v89, v0
	v_mov_b32_e32 v90, v0
	v_mov_b32_e32 v91, v0
	v_mov_b32_e32 v92, v0
	v_mov_b32_e32 v93, v0
	v_mov_b32_e32 v94, v0
	v_mov_b32_e32 v95, v0
	v_mov_b32_e32 v96, v0
	v_mov_b32_e32 v97, v0
	v_mov_b32_e32 v98, v0
	v_mov_b32_e32 v99, v0
	v_mov_b32_e32 v100, v0
	v_mov_b32_e32 v101, v0
	v_mov_b32_e32 v102, v0
	v_mov_b32_e32 v103, v0
	v_mov_b32_e32 v104, v0
	v_mov_b32_e32 v105, v0
	v_mov_b32_e32 v106, v0
	v_mov_b32_e32 v107, v0
	v_mov_b32_e32 v108, v0
	v_mov_b32_e32 v109, v0
	v_mov_b32_e32 v110, v0
	v_mov_b32_e32 v111, v0
	v_mov_b32_e32 v112, v0
	v_mov_b32_e32 v113, v0
	v_mov_b32_e32 v114, v0
	v_mov_b32_e32 v115, v0
	v_mov_b32_e32 v116, v0
	v_mov_b32_e32 v117, v0
	v_mov_b32_e32 v118, v0
	v_mov_b32_e32 v119, v0
	v_mov_b32_e32 v120, v0
	v_mov_b32_e32 v121, v0
	v_mov_b32_e32 v122, v0
	v_mov_b32_e32 v123, v0
	v_mov_b32_e32 v124, v0
	v_mov_b32_e32 v125, v0
	v_mov_b32_e32 v126, v0
	v_mov_b32_e32 v127, v0
	v_lshrrev_b32_e32 v222, 8, v182
	v_cmp_eq_u32_e32 vcc, 1, v222
	s_and_saveexec_b64 s[42:43], vcc
	s_cbranch_execz .Lg5_nba
	s_barrier
